# placement sweep: both attention loop heads at 32 mod 64
# baseline (speedup 1.0000x reference)
.LBB0_505:
	v_add_f32_e32 v16, 0, v32
	v_add_f32_e32 v16, v33, v16
	v_add_f32_e32 v17, 0, v40
	v_add_f32_e32 v16, v34, v16
	v_add_f32_e32 v17, v41, v17
	v_add_f32_e32 v16, v35, v16
	v_add_f32_e32 v17, v42, v17
	v_add_f32_e32 v16, v36, v16
	v_add_f32_e32 v17, v43, v17
	v_add_f32_e32 v16, v37, v16
	v_add_f32_e32 v17, v44, v17
	v_add_f32_e32 v16, v38, v16
	v_add_f32_e32 v17, v45, v17
	v_add_f32_e32 v16, v39, v16
	v_add_f32_e32 v17, v46, v17
	v_add_f32_e32 v16, 0, v16
	v_add_f32_e32 v17, v47, v17
	v_add_f32_e32 v18, 0, v48
	v_add_f32_e32 v16, v17, v16
	v_add_f32_e32 v17, 0, v56
	v_add_f32_e32 v18, v49, v18
	v_add_f32_e32 v17, v57, v17
	v_add_f32_e32 v18, v50, v18
	v_add_f32_e32 v17, v58, v17
	v_add_f32_e32 v18, v51, v18
	v_add_f32_e32 v17, v59, v17
	v_add_f32_e32 v18, v52, v18
	v_add_f32_e32 v17, v60, v17
	v_add_f32_e32 v18, v53, v18
	v_add_f32_e32 v17, v61, v17
	v_add_f32_e32 v18, v54, v18
	s_waitcnt vmcnt(0)
	ds_write_b64 v216, v[64:65] offset:18432
	s_waitcnt lgkmcnt(0)
	ds_write_b64 v216, v[68:69] offset:27648
	ds_write2st64_b64 v217, v[66:67], v[70:71] offset0:36 offset1:54
	ds_write_b128 v213, v[144:147]
	v_add_f32_e32 v17, v62, v17
	v_add_f32_e32 v18, v55, v18
	s_waitcnt lgkmcnt(0)
	s_barrier
	v_add_f32_e32 v17, v63, v17
	v_add_f32_e32 v16, v18, v16
	v_mov_b32_e32 v31, 0
	v_cvt_pk_bf16_f32 v160, v32, v33
	v_cvt_pk_bf16_f32 v161, v34, v35
	v_cvt_pk_bf16_f32 v162, v36, v37
	v_cvt_pk_bf16_f32 v163, v38, v39
	v_cvt_pk_bf16_f32 v148, v40, v41
	v_cvt_pk_bf16_f32 v149, v42, v43
	v_cvt_pk_bf16_f32 v150, v44, v45
	v_cvt_pk_bf16_f32 v151, v46, v47
	v_cvt_pk_bf16_f32 v152, v48, v49
	v_cvt_pk_bf16_f32 v153, v50, v51
	v_cvt_pk_bf16_f32 v154, v52, v53
	v_cvt_pk_bf16_f32 v155, v54, v55
	v_add_f32_e32 v193, v17, v16
	v_cvt_pk_bf16_f32 v156, v56, v57
	v_cvt_pk_bf16_f32 v157, v58, v59
	v_cvt_pk_bf16_f32 v158, v60, v61
	v_cvt_pk_bf16_f32 v159, v62, v63
	s_andn2_b64 vcc, exec, s[2:3]
	s_cbranch_vccnz .LBB0_512
	v_mov_b32_e32 v32, 0
	s_mov_b32 s93, 0
	s_movk_i32 s15, 0x80
	s_mov_b64 s[6:7], 0x80
	v_mov_b32_e32 v33, v32
	v_mov_b32_e32 v34, v32
	v_mov_b32_e32 v35, v32
	v_mov_b32_e32 v36, v32
	v_mov_b32_e32 v37, v32
	v_mov_b32_e32 v38, v32
	v_mov_b32_e32 v39, v32
	v_mov_b32_e32 v40, v32
	v_mov_b32_e32 v41, v32
	v_mov_b32_e32 v42, v32
	v_mov_b32_e32 v43, v32
	v_mov_b32_e32 v44, v32
	v_mov_b32_e32 v45, v32
	v_mov_b32_e32 v46, v32
	v_mov_b32_e32 v47, v32
	v_mov_b32_e32 v64, v32
	v_mov_b32_e32 v65, v32
	v_mov_b32_e32 v66, v32
	v_mov_b32_e32 v67, v32
	v_mov_b32_e32 v68, v32
	v_mov_b32_e32 v69, v32
	v_mov_b32_e32 v70, v32
	v_mov_b32_e32 v71, v32
	v_mov_b32_e32 v72, v32
	v_mov_b32_e32 v73, v32
	v_mov_b32_e32 v74, v32
	v_mov_b32_e32 v75, v32
	v_mov_b32_e32 v76, v32
	v_mov_b32_e32 v77, v32
	v_mov_b32_e32 v78, v32
	v_mov_b32_e32 v79, v32
	v_mov_b32_e32 v48, v32
	v_mov_b32_e32 v49, v32
	v_mov_b32_e32 v50, v32
	v_mov_b32_e32 v51, v32
	v_mov_b32_e32 v52, v32
	v_mov_b32_e32 v53, v32
	v_mov_b32_e32 v54, v32
	v_mov_b32_e32 v55, v32
	v_mov_b32_e32 v56, v32
	v_mov_b32_e32 v57, v32
	v_mov_b32_e32 v58, v32
	v_mov_b32_e32 v59, v32
	v_mov_b32_e32 v60, v32
	v_mov_b32_e32 v61, v32
	v_mov_b32_e32 v62, v32
	v_mov_b32_e32 v63, v32
	v_mov_b32_e32 v16, v32
	v_mov_b32_e32 v17, v32
	v_mov_b32_e32 v18, v32
	v_mov_b32_e32 v19, v32
	v_mov_b32_e32 v20, v32
	v_mov_b32_e32 v21, v32
	v_mov_b32_e32 v22, v32
	v_mov_b32_e32 v23, v32
	v_mov_b32_e32 v24, v32
	v_mov_b32_e32 v25, v32
	v_mov_b32_e32 v26, v32
	v_mov_b32_e32 v27, v32
	v_mov_b32_e32 v28, v32
	v_mov_b32_e32 v29, v32
	v_mov_b32_e32 v30, v32
	v_mov_b32_e32 v31, v32
	v_mov_b32_e32 v142, 0
	s_branch .LBB0_508
	.p2align 6
	s_nop 0
	s_nop 0
	s_nop 0
	s_nop 0
	s_nop 0
	s_nop 0
	s_nop 0
	s_nop 0

.LBB0_539:
	v_add_f32_e32 v16, 0, v32
	v_add_f32_e32 v16, v33, v16
	v_add_f32_e32 v17, 0, v40
	v_add_f32_e32 v16, v34, v16
	v_add_f32_e32 v17, v41, v17
	v_add_f32_e32 v16, v35, v16
	v_add_f32_e32 v17, v42, v17
	v_add_f32_e32 v16, v36, v16
	v_add_f32_e32 v17, v43, v17
	v_add_f32_e32 v16, v37, v16
	v_add_f32_e32 v17, v44, v17
	v_add_f32_e32 v16, v38, v16
	v_add_f32_e32 v17, v45, v17
	v_add_f32_e32 v16, v39, v16
	v_add_f32_e32 v17, v46, v17
	v_add_f32_e32 v16, 0, v16
	v_add_f32_e32 v17, v47, v17
	v_add_f32_e32 v18, 0, v48
	v_add_f32_e32 v16, v17, v16
	v_add_f32_e32 v17, 0, v56
	v_add_f32_e32 v18, v49, v18
	v_add_f32_e32 v17, v57, v17
	v_add_f32_e32 v18, v50, v18
	v_add_f32_e32 v17, v58, v17
	v_add_f32_e32 v18, v51, v18
	v_add_f32_e32 v17, v59, v17
	v_add_f32_e32 v18, v52, v18
	v_add_f32_e32 v17, v60, v17
	v_add_f32_e32 v18, v53, v18
	v_add_f32_e32 v17, v61, v17
	v_add_f32_e32 v18, v54, v18
	s_waitcnt vmcnt(0)
	ds_write_b64 v216, v[64:65] offset:18432
	s_waitcnt lgkmcnt(0)
	ds_write_b64 v216, v[68:69] offset:27648
	ds_write2st64_b64 v217, v[66:67], v[70:71] offset0:36 offset1:54
	ds_write_b128 v213, v[144:147]
	v_add_f32_e32 v17, v62, v17
	v_add_f32_e32 v18, v55, v18
	s_waitcnt lgkmcnt(0)
	s_barrier
	v_add_f32_e32 v17, v63, v17
	v_add_f32_e32 v16, v18, v16
	v_mov_b32_e32 v31, 0
	v_cvt_pk_bf16_f32 v160, v32, v33
	v_cvt_pk_bf16_f32 v161, v34, v35
	v_cvt_pk_bf16_f32 v162, v36, v37
	v_cvt_pk_bf16_f32 v163, v38, v39
	v_cvt_pk_bf16_f32 v148, v40, v41
	v_cvt_pk_bf16_f32 v149, v42, v43
	v_cvt_pk_bf16_f32 v150, v44, v45
	v_cvt_pk_bf16_f32 v151, v46, v47
	v_cvt_pk_bf16_f32 v152, v48, v49
	v_cvt_pk_bf16_f32 v153, v50, v51
	v_cvt_pk_bf16_f32 v154, v52, v53
	v_cvt_pk_bf16_f32 v155, v54, v55
	v_add_f32_e32 v193, v17, v16
	v_cvt_pk_bf16_f32 v156, v56, v57
	v_cvt_pk_bf16_f32 v157, v58, v59
	v_cvt_pk_bf16_f32 v158, v60, v61
	v_cvt_pk_bf16_f32 v159, v62, v63
	s_andn2_b64 vcc, exec, s[80:81]
	s_cbranch_vccnz .LBB0_546
	v_mov_b32_e32 v32, 0
	s_mov_b32 s77, 0
	s_movk_i32 s15, 0x80
	s_mov_b64 s[6:7], 0x80
	v_mov_b32_e32 v33, v32
	v_mov_b32_e32 v34, v32
	v_mov_b32_e32 v35, v32
	v_mov_b32_e32 v36, v32
	v_mov_b32_e32 v37, v32
	v_mov_b32_e32 v38, v32
	v_mov_b32_e32 v39, v32
	v_mov_b32_e32 v40, v32
	v_mov_b32_e32 v41, v32
	v_mov_b32_e32 v42, v32
	v_mov_b32_e32 v43, v32
	v_mov_b32_e32 v44, v32
	v_mov_b32_e32 v45, v32
	v_mov_b32_e32 v46, v32
	v_mov_b32_e32 v47, v32
	v_mov_b32_e32 v64, v32
	v_mov_b32_e32 v65, v32
	v_mov_b32_e32 v66, v32
	v_mov_b32_e32 v67, v32
	v_mov_b32_e32 v68, v32
	v_mov_b32_e32 v69, v32
	v_mov_b32_e32 v70, v32
	v_mov_b32_e32 v71, v32
	v_mov_b32_e32 v72, v32
	v_mov_b32_e32 v73, v32
	v_mov_b32_e32 v74, v32
	v_mov_b32_e32 v75, v32
	v_mov_b32_e32 v76, v32
	v_mov_b32_e32 v77, v32
	v_mov_b32_e32 v78, v32
	v_mov_b32_e32 v79, v32
	v_mov_b32_e32 v48, v32
	v_mov_b32_e32 v49, v32
	v_mov_b32_e32 v50, v32
	v_mov_b32_e32 v51, v32
	v_mov_b32_e32 v52, v32
	v_mov_b32_e32 v53, v32
	v_mov_b32_e32 v54, v32
	v_mov_b32_e32 v55, v32
	v_mov_b32_e32 v56, v32
	v_mov_b32_e32 v57, v32
	v_mov_b32_e32 v58, v32
	v_mov_b32_e32 v59, v32
	v_mov_b32_e32 v60, v32
	v_mov_b32_e32 v61, v32
	v_mov_b32_e32 v62, v32
	v_mov_b32_e32 v63, v32
	v_mov_b32_e32 v16, v32
	v_mov_b32_e32 v17, v32
	v_mov_b32_e32 v18, v32
	v_mov_b32_e32 v19, v32
	v_mov_b32_e32 v20, v32
	v_mov_b32_e32 v21, v32
	v_mov_b32_e32 v22, v32
	v_mov_b32_e32 v23, v32
	v_mov_b32_e32 v24, v32
	v_mov_b32_e32 v25, v32
	v_mov_b32_e32 v26, v32
	v_mov_b32_e32 v27, v32
	v_mov_b32_e32 v28, v32
	v_mov_b32_e32 v29, v32
	v_mov_b32_e32 v30, v32
	v_mov_b32_e32 v31, v32
	v_mov_b32_e32 v142, 0
	s_branch .LBB0_542
	.p2align 6
	s_nop 0
	s_nop 0
	s_nop 0
	s_nop 0
	s_nop 0
	s_nop 0
	s_nop 0
	s_nop 0
